# mla_in k_r rope epilogue: cos/sin prefetch ring, stores at end
# baseline (speedup 1.0000x reference)
.LBB0_947:
	s_andn2_saveexec_b64 s[60:61], s[60:61]
	s_cbranch_execz .LBB0_949
	v_or_b32_e32 v141, v130, v144
	v_lshlrev_b32_e32 v142, 7, v141
	v_lshl_add_u32 v142, v128, 2, v142
	v_mad_i64_i32 v[160:161], s[20:21], v141, s68, v[134:135]
	global_load_dword v182, v142, s[10:11]
	global_load_dword v190, v142, s[12:13]
	global_load_dword v183, v142, s[10:11] offset:128
	global_load_dword v191, v142, s[12:13] offset:128
	global_load_dword v184, v142, s[10:11] offset:256
	global_load_dword v192, v142, s[12:13] offset:256
	global_load_dword v185, v142, s[10:11] offset:384
	global_load_dword v193, v142, s[12:13] offset:384
	global_load_dword v186, v142, s[10:11] offset:64
	global_load_dword v194, v142, s[12:13] offset:64
	global_load_dword v187, v142, s[10:11] offset:192
	global_load_dword v195, v142, s[12:13] offset:192
	global_load_dword v188, v142, s[10:11] offset:320
	global_load_dword v196, v142, s[12:13] offset:320
	global_load_dword v189, v142, s[10:11] offset:448
	global_load_dword v197, v142, s[12:13] offset:448
	v_add_u32_e32 v143, 0x800, v142
	global_load_dword v198, v143, s[10:11]
	global_load_dword v206, v143, s[12:13]
	global_load_dword v199, v143, s[10:11] offset:128
	global_load_dword v207, v143, s[12:13] offset:128
	global_load_dword v200, v143, s[10:11] offset:256
	global_load_dword v208, v143, s[12:13] offset:256
	global_load_dword v201, v143, s[10:11] offset:384
	global_load_dword v209, v143, s[12:13] offset:384
	global_load_dword v202, v143, s[10:11] offset:64
	global_load_dword v210, v143, s[12:13] offset:64
	global_load_dword v203, v143, s[10:11] offset:192
	global_load_dword v211, v143, s[12:13] offset:192
	global_load_dword v204, v143, s[10:11] offset:320
	global_load_dword v212, v143, s[12:13] offset:320
	global_load_dword v205, v143, s[10:11] offset:448
	global_load_dword v213, v143, s[12:13] offset:448
	v_add_u32_e32 v143, 0x1000, v142
	global_load_dword v214, v143, s[10:11]
	global_load_dword v222, v143, s[12:13]
	global_load_dword v215, v143, s[10:11] offset:128
	global_load_dword v223, v143, s[12:13] offset:128
	global_load_dword v216, v143, s[10:11] offset:256
	global_load_dword v224, v143, s[12:13] offset:256
	global_load_dword v217, v143, s[10:11] offset:384
	global_load_dword v225, v143, s[12:13] offset:384
	global_load_dword v218, v143, s[10:11] offset:64
	global_load_dword v226, v143, s[12:13] offset:64
	global_load_dword v219, v143, s[10:11] offset:192
	global_load_dword v227, v143, s[12:13] offset:192
	global_load_dword v220, v143, s[10:11] offset:320
	global_load_dword v228, v143, s[12:13] offset:320
	global_load_dword v221, v143, s[10:11] offset:448
	global_load_dword v229, v143, s[12:13] offset:448
	v_add_u32_e32 v143, 0x1800, v142
	global_load_dword v230, v143, s[10:11]
	global_load_dword v238, v143, s[12:13]
	global_load_dword v231, v143, s[10:11] offset:128
	global_load_dword v239, v143, s[12:13] offset:128
	global_load_dword v232, v143, s[10:11] offset:256
	global_load_dword v240, v143, s[12:13] offset:256
	global_load_dword v233, v143, s[10:11] offset:384
	global_load_dword v241, v143, s[12:13] offset:384
	global_load_dword v234, v143, s[10:11] offset:64
	global_load_dword v242, v143, s[12:13] offset:64
	global_load_dword v235, v143, s[10:11] offset:192
	global_load_dword v243, v143, s[12:13] offset:192
	global_load_dword v236, v143, s[10:11] offset:320
	global_load_dword v244, v143, s[12:13] offset:320
	global_load_dword v237, v143, s[10:11] offset:448
	global_load_dword v245, v143, s[12:13] offset:448
	v_add_u32_e32 v143, 0x2000, v142
	global_load_dword v246, v143, s[10:11]
	global_load_dword v151, v143, s[12:13]
	global_load_dword v247, v143, s[10:11] offset:128
	global_load_dword v152, v143, s[12:13] offset:128
	global_load_dword v248, v143, s[10:11] offset:256
	global_load_dword v153, v143, s[12:13] offset:256
	global_load_dword v249, v143, s[10:11] offset:384
	global_load_dword v154, v143, s[12:13] offset:384
	global_load_dword v250, v143, s[10:11] offset:64
	global_load_dword v155, v143, s[12:13] offset:64
	global_load_dword v251, v143, s[10:11] offset:192
	global_load_dword v156, v143, s[12:13] offset:192
	global_load_dword v149, v143, s[10:11] offset:320
	global_load_dword v157, v143, s[12:13] offset:320
	global_load_dword v150, v143, s[10:11] offset:448
	global_load_dword v158, v143, s[12:13] offset:448
	s_waitcnt vmcnt(63)
	v_mul_f32_e32 v162, v116, v190
	v_mul_f32_e32 v163, v124, v190
	v_fma_f32 v162, v124, v182, -v162
	v_fmac_f32_e32 v163, v116, v182
	v_mul_f32_e32 v164, v117, v191
	v_mul_f32_e32 v165, v125, v191
	v_fma_f32 v164, v125, v183, -v164
	v_fmac_f32_e32 v165, v117, v183
	v_cvt_pk_bf16_f32 v124, v162, v164
	v_cvt_pk_bf16_f32 v116, v163, v165
	v_mul_f32_e32 v162, v118, v192
	v_mul_f32_e32 v163, v126, v192
	v_fma_f32 v162, v126, v184, -v162
	v_fmac_f32_e32 v163, v118, v184
	v_mul_f32_e32 v164, v119, v193
	v_mul_f32_e32 v165, v127, v193
	v_fma_f32 v164, v127, v185, -v164
	v_fmac_f32_e32 v165, v119, v185
	v_cvt_pk_bf16_f32 v126, v162, v164
	v_cvt_pk_bf16_f32 v118, v163, v165
	v_mul_f32_e32 v162, v112, v194
	v_mul_f32_e32 v163, v120, v194
	v_fma_f32 v162, v120, v186, -v162
	v_fmac_f32_e32 v163, v112, v186
	v_mul_f32_e32 v164, v113, v195
	v_mul_f32_e32 v165, v121, v195
	v_fma_f32 v164, v121, v187, -v164
	v_fmac_f32_e32 v165, v113, v187
	v_cvt_pk_bf16_f32 v120, v162, v164
	v_cvt_pk_bf16_f32 v112, v163, v165
	v_mul_f32_e32 v162, v114, v196
	v_mul_f32_e32 v163, v122, v196
	v_fma_f32 v162, v122, v188, -v162
	v_fmac_f32_e32 v163, v114, v188
	v_mul_f32_e32 v164, v115, v197
	v_mul_f32_e32 v165, v123, v197
	v_fma_f32 v164, v123, v189, -v164
	v_fmac_f32_e32 v165, v115, v189
	v_cvt_pk_bf16_f32 v122, v162, v164
	v_cvt_pk_bf16_f32 v114, v163, v165
	v_add_u32_e32 v143, 0x2800, v142
	global_load_dword v182, v143, s[10:11]
	global_load_dword v190, v143, s[12:13]
	global_load_dword v183, v143, s[10:11] offset:128
	global_load_dword v191, v143, s[12:13] offset:128
	global_load_dword v184, v143, s[10:11] offset:256
	global_load_dword v192, v143, s[12:13] offset:256
	global_load_dword v185, v143, s[10:11] offset:384
	global_load_dword v193, v143, s[12:13] offset:384
	global_load_dword v186, v143, s[10:11] offset:64
	global_load_dword v194, v143, s[12:13] offset:64
	global_load_dword v187, v143, s[10:11] offset:192
	global_load_dword v195, v143, s[12:13] offset:192
	global_load_dword v188, v143, s[10:11] offset:320
	global_load_dword v196, v143, s[12:13] offset:320
	global_load_dword v189, v143, s[10:11] offset:448
	global_load_dword v197, v143, s[12:13] offset:448
	s_waitcnt vmcnt(63)
	v_mul_f32_e32 v162, v100, v206
	v_mul_f32_e32 v163, v108, v206
	v_fma_f32 v162, v108, v198, -v162
	v_fmac_f32_e32 v163, v100, v198
	v_mul_f32_e32 v164, v101, v207
	v_mul_f32_e32 v165, v109, v207
	v_fma_f32 v164, v109, v199, -v164
	v_fmac_f32_e32 v165, v101, v199
	v_cvt_pk_bf16_f32 v108, v162, v164
	v_cvt_pk_bf16_f32 v100, v163, v165
	v_mul_f32_e32 v162, v102, v208
	v_mul_f32_e32 v163, v110, v208
	v_fma_f32 v162, v110, v200, -v162
	v_fmac_f32_e32 v163, v102, v200
	v_mul_f32_e32 v164, v103, v209
	v_mul_f32_e32 v165, v111, v209
	v_fma_f32 v164, v111, v201, -v164
	v_fmac_f32_e32 v165, v103, v201
	v_cvt_pk_bf16_f32 v110, v162, v164
	v_cvt_pk_bf16_f32 v102, v163, v165
	v_mul_f32_e32 v162, v96, v210
	v_mul_f32_e32 v163, v104, v210
	v_fma_f32 v162, v104, v202, -v162
	v_fmac_f32_e32 v163, v96, v202
	v_mul_f32_e32 v164, v97, v211
	v_mul_f32_e32 v165, v105, v211
	v_fma_f32 v164, v105, v203, -v164
	v_fmac_f32_e32 v165, v97, v203
	v_cvt_pk_bf16_f32 v104, v162, v164
	v_cvt_pk_bf16_f32 v96, v163, v165
	v_mul_f32_e32 v162, v98, v212
	v_mul_f32_e32 v163, v106, v212
	v_fma_f32 v162, v106, v204, -v162
	v_fmac_f32_e32 v163, v98, v204
	v_mul_f32_e32 v164, v99, v213
	v_mul_f32_e32 v165, v107, v213
	v_fma_f32 v164, v107, v205, -v164
	v_fmac_f32_e32 v165, v99, v205
	v_cvt_pk_bf16_f32 v106, v162, v164
	v_cvt_pk_bf16_f32 v98, v163, v165
	v_add_u32_e32 v143, 0x3000, v142
	global_load_dword v198, v143, s[10:11]
	global_load_dword v206, v143, s[12:13]
	global_load_dword v199, v143, s[10:11] offset:128
	global_load_dword v207, v143, s[12:13] offset:128
	global_load_dword v200, v143, s[10:11] offset:256
	global_load_dword v208, v143, s[12:13] offset:256
	global_load_dword v201, v143, s[10:11] offset:384
	global_load_dword v209, v143, s[12:13] offset:384
	global_load_dword v202, v143, s[10:11] offset:64
	global_load_dword v210, v143, s[12:13] offset:64
	global_load_dword v203, v143, s[10:11] offset:192
	global_load_dword v211, v143, s[12:13] offset:192
	global_load_dword v204, v143, s[10:11] offset:320
	global_load_dword v212, v143, s[12:13] offset:320
	global_load_dword v205, v143, s[10:11] offset:448
	global_load_dword v213, v143, s[12:13] offset:448
	s_waitcnt vmcnt(63)
	v_mul_f32_e32 v162, v84, v222
	v_mul_f32_e32 v163, v92, v222
	v_fma_f32 v162, v92, v214, -v162
	v_fmac_f32_e32 v163, v84, v214
	v_mul_f32_e32 v164, v85, v223
	v_mul_f32_e32 v165, v93, v223
	v_fma_f32 v164, v93, v215, -v164
	v_fmac_f32_e32 v165, v85, v215
	v_cvt_pk_bf16_f32 v92, v162, v164
	v_cvt_pk_bf16_f32 v84, v163, v165
	v_mul_f32_e32 v162, v86, v224
	v_mul_f32_e32 v163, v94, v224
	v_fma_f32 v162, v94, v216, -v162
	v_fmac_f32_e32 v163, v86, v216
	v_mul_f32_e32 v164, v87, v225
	v_mul_f32_e32 v165, v95, v225
	v_fma_f32 v164, v95, v217, -v164
	v_fmac_f32_e32 v165, v87, v217
	v_cvt_pk_bf16_f32 v94, v162, v164
	v_cvt_pk_bf16_f32 v86, v163, v165
	v_mul_f32_e32 v162, v80, v226
	v_mul_f32_e32 v163, v88, v226
	v_fma_f32 v162, v88, v218, -v162
	v_fmac_f32_e32 v163, v80, v218
	v_mul_f32_e32 v164, v81, v227
	v_mul_f32_e32 v165, v89, v227
	v_fma_f32 v164, v89, v219, -v164
	v_fmac_f32_e32 v165, v81, v219
	v_cvt_pk_bf16_f32 v88, v162, v164
	v_cvt_pk_bf16_f32 v80, v163, v165
	v_mul_f32_e32 v162, v82, v228
	v_mul_f32_e32 v163, v90, v228
	v_fma_f32 v162, v90, v220, -v162
	v_fmac_f32_e32 v163, v82, v220
	v_mul_f32_e32 v164, v83, v229
	v_mul_f32_e32 v165, v91, v229
	v_fma_f32 v164, v91, v221, -v164
	v_fmac_f32_e32 v165, v83, v221
	v_cvt_pk_bf16_f32 v90, v162, v164
	v_cvt_pk_bf16_f32 v82, v163, v165
	v_add_u32_e32 v143, 0x3800, v142
	global_load_dword v214, v143, s[10:11]
	global_load_dword v222, v143, s[12:13]
	global_load_dword v215, v143, s[10:11] offset:128
	global_load_dword v223, v143, s[12:13] offset:128
	global_load_dword v216, v143, s[10:11] offset:256
	global_load_dword v224, v143, s[12:13] offset:256
	global_load_dword v217, v143, s[10:11] offset:384
	global_load_dword v225, v143, s[12:13] offset:384
	global_load_dword v218, v143, s[10:11] offset:64
	global_load_dword v226, v143, s[12:13] offset:64
	global_load_dword v219, v143, s[10:11] offset:192
	global_load_dword v227, v143, s[12:13] offset:192
	global_load_dword v220, v143, s[10:11] offset:320
	global_load_dword v228, v143, s[12:13] offset:320
	global_load_dword v221, v143, s[10:11] offset:448
	global_load_dword v229, v143, s[12:13] offset:448
	s_waitcnt vmcnt(63)
	v_mul_f32_e32 v162, v68, v238
	v_mul_f32_e32 v163, v76, v238
	v_fma_f32 v162, v76, v230, -v162
	v_fmac_f32_e32 v163, v68, v230
	v_mul_f32_e32 v164, v69, v239
	v_mul_f32_e32 v165, v77, v239
	v_fma_f32 v164, v77, v231, -v164
	v_fmac_f32_e32 v165, v69, v231
	v_cvt_pk_bf16_f32 v76, v162, v164
	v_cvt_pk_bf16_f32 v68, v163, v165
	v_mul_f32_e32 v162, v70, v240
	v_mul_f32_e32 v163, v78, v240
	v_fma_f32 v162, v78, v232, -v162
	v_fmac_f32_e32 v163, v70, v232
	v_mul_f32_e32 v164, v71, v241
	v_mul_f32_e32 v165, v79, v241
	v_fma_f32 v164, v79, v233, -v164
	v_fmac_f32_e32 v165, v71, v233
	v_cvt_pk_bf16_f32 v78, v162, v164
	v_cvt_pk_bf16_f32 v70, v163, v165
	v_mul_f32_e32 v162, v64, v242
	v_mul_f32_e32 v163, v72, v242
	v_fma_f32 v162, v72, v234, -v162
	v_fmac_f32_e32 v163, v64, v234
	v_mul_f32_e32 v164, v65, v243
	v_mul_f32_e32 v165, v73, v243
	v_fma_f32 v164, v73, v235, -v164
	v_fmac_f32_e32 v165, v65, v235
	v_cvt_pk_bf16_f32 v72, v162, v164
	v_cvt_pk_bf16_f32 v64, v163, v165
	v_mul_f32_e32 v162, v66, v244
	v_mul_f32_e32 v163, v74, v244
	v_fma_f32 v162, v74, v236, -v162
	v_fmac_f32_e32 v163, v66, v236
	v_mul_f32_e32 v164, v67, v245
	v_mul_f32_e32 v165, v75, v245
	v_fma_f32 v164, v75, v237, -v164
	v_fmac_f32_e32 v165, v67, v237
	v_cvt_pk_bf16_f32 v74, v162, v164
	v_cvt_pk_bf16_f32 v66, v163, v165
	s_waitcnt vmcnt(48)
	v_mul_f32_e32 v162, v52, v151
	v_mul_f32_e32 v163, v60, v151
	v_fma_f32 v162, v60, v246, -v162
	v_fmac_f32_e32 v163, v52, v246
	v_mul_f32_e32 v164, v53, v152
	v_mul_f32_e32 v165, v61, v152
	v_fma_f32 v164, v61, v247, -v164
	v_fmac_f32_e32 v165, v53, v247
	v_cvt_pk_bf16_f32 v60, v162, v164
	v_cvt_pk_bf16_f32 v52, v163, v165
	v_mul_f32_e32 v162, v54, v153
	v_mul_f32_e32 v163, v62, v153
	v_fma_f32 v162, v62, v248, -v162
	v_fmac_f32_e32 v163, v54, v248
	v_mul_f32_e32 v164, v55, v154
	v_mul_f32_e32 v165, v63, v154
	v_fma_f32 v164, v63, v249, -v164
	v_fmac_f32_e32 v165, v55, v249
	v_cvt_pk_bf16_f32 v62, v162, v164
	v_cvt_pk_bf16_f32 v54, v163, v165
	v_mul_f32_e32 v162, v44, v155
	v_mul_f32_e32 v163, v56, v155
	v_fma_f32 v162, v56, v250, -v162
	v_fmac_f32_e32 v163, v44, v250
	v_mul_f32_e32 v164, v45, v156
	v_mul_f32_e32 v165, v57, v156
	v_fma_f32 v164, v57, v251, -v164
	v_fmac_f32_e32 v165, v45, v251
	v_cvt_pk_bf16_f32 v56, v162, v164
	v_cvt_pk_bf16_f32 v44, v163, v165
	v_mul_f32_e32 v162, v46, v157
	v_mul_f32_e32 v163, v58, v157
	v_fma_f32 v162, v58, v149, -v162
	v_fmac_f32_e32 v163, v46, v149
	v_mul_f32_e32 v164, v47, v158
	v_mul_f32_e32 v165, v59, v158
	v_fma_f32 v164, v59, v150, -v164
	v_fmac_f32_e32 v165, v47, v150
	v_cvt_pk_bf16_f32 v58, v162, v164
	v_cvt_pk_bf16_f32 v46, v163, v165
	s_waitcnt vmcnt(32)
	v_mul_f32_e32 v162, v28, v190
	v_mul_f32_e32 v163, v36, v190
	v_fma_f32 v162, v36, v182, -v162
	v_fmac_f32_e32 v163, v28, v182
	v_mul_f32_e32 v164, v29, v191
	v_mul_f32_e32 v165, v37, v191
	v_fma_f32 v164, v37, v183, -v164
	v_fmac_f32_e32 v165, v29, v183
	v_cvt_pk_bf16_f32 v36, v162, v164
	v_cvt_pk_bf16_f32 v28, v163, v165
	v_mul_f32_e32 v162, v30, v192
	v_mul_f32_e32 v163, v38, v192
	v_fma_f32 v162, v38, v184, -v162
	v_fmac_f32_e32 v163, v30, v184
	v_mul_f32_e32 v164, v31, v193
	v_mul_f32_e32 v165, v39, v193
	v_fma_f32 v164, v39, v185, -v164
	v_fmac_f32_e32 v165, v31, v185
	v_cvt_pk_bf16_f32 v38, v162, v164
	v_cvt_pk_bf16_f32 v30, v163, v165
	v_mul_f32_e32 v162, v24, v194
	v_mul_f32_e32 v163, v32, v194
	v_fma_f32 v162, v32, v186, -v162
	v_fmac_f32_e32 v163, v24, v186
	v_mul_f32_e32 v164, v25, v195
	v_mul_f32_e32 v165, v33, v195
	v_fma_f32 v164, v33, v187, -v164
	v_fmac_f32_e32 v165, v25, v187
	v_cvt_pk_bf16_f32 v32, v162, v164
	v_cvt_pk_bf16_f32 v24, v163, v165
	v_mul_f32_e32 v162, v26, v196
	v_mul_f32_e32 v163, v34, v196
	v_fma_f32 v162, v34, v188, -v162
	v_fmac_f32_e32 v163, v26, v188
	v_mul_f32_e32 v164, v27, v197
	v_mul_f32_e32 v165, v35, v197
	v_fma_f32 v164, v35, v189, -v164
	v_fmac_f32_e32 v165, v27, v189
	v_cvt_pk_bf16_f32 v34, v162, v164
	v_cvt_pk_bf16_f32 v26, v163, v165
	s_waitcnt vmcnt(16)
	v_mul_f32_e32 v162, v12, v206
	v_mul_f32_e32 v163, v20, v206
	v_fma_f32 v162, v20, v198, -v162
	v_fmac_f32_e32 v163, v12, v198
	v_mul_f32_e32 v164, v13, v207
	v_mul_f32_e32 v165, v21, v207
	v_fma_f32 v164, v21, v199, -v164
	v_fmac_f32_e32 v165, v13, v199
	v_cvt_pk_bf16_f32 v20, v162, v164
	v_cvt_pk_bf16_f32 v12, v163, v165
	v_mul_f32_e32 v162, v14, v208
	v_mul_f32_e32 v163, v22, v208
	v_fma_f32 v162, v22, v200, -v162
	v_fmac_f32_e32 v163, v14, v200
	v_mul_f32_e32 v164, v15, v209
	v_mul_f32_e32 v165, v23, v209
	v_fma_f32 v164, v23, v201, -v164
	v_fmac_f32_e32 v165, v15, v201
	v_cvt_pk_bf16_f32 v22, v162, v164
	v_cvt_pk_bf16_f32 v14, v163, v165
	v_mul_f32_e32 v162, v8, v210
	v_mul_f32_e32 v163, v16, v210
	v_fma_f32 v162, v16, v202, -v162
	v_fmac_f32_e32 v163, v8, v202
	v_mul_f32_e32 v164, v9, v211
	v_mul_f32_e32 v165, v17, v211
	v_fma_f32 v164, v17, v203, -v164
	v_fmac_f32_e32 v165, v9, v203
	v_cvt_pk_bf16_f32 v16, v162, v164
	v_cvt_pk_bf16_f32 v8, v163, v165
	v_mul_f32_e32 v162, v10, v212
	v_mul_f32_e32 v163, v18, v212
	v_fma_f32 v162, v18, v204, -v162
	v_fmac_f32_e32 v163, v10, v204
	v_mul_f32_e32 v164, v11, v213
	v_mul_f32_e32 v165, v19, v213
	v_fma_f32 v164, v19, v205, -v164
	v_fmac_f32_e32 v165, v11, v205
	v_cvt_pk_bf16_f32 v18, v162, v164
	v_cvt_pk_bf16_f32 v10, v163, v165
	s_waitcnt vmcnt(0)
	v_mul_f32_e32 v162, v48, v222
	v_mul_f32_e32 v163, v4, v222
	v_fma_f32 v162, v4, v214, -v162
	v_fmac_f32_e32 v163, v48, v214
	v_mul_f32_e32 v164, v49, v223
	v_mul_f32_e32 v165, v5, v223
	v_fma_f32 v164, v5, v215, -v164
	v_fmac_f32_e32 v165, v49, v215
	v_cvt_pk_bf16_f32 v4, v162, v164
	v_cvt_pk_bf16_f32 v48, v163, v165
	v_mul_f32_e32 v162, v50, v224
	v_mul_f32_e32 v163, v6, v224
	v_fma_f32 v162, v6, v216, -v162
	v_fmac_f32_e32 v163, v50, v216
	v_mul_f32_e32 v164, v51, v225
	v_mul_f32_e32 v165, v7, v225
	v_fma_f32 v164, v7, v217, -v164
	v_fmac_f32_e32 v165, v51, v217
	v_cvt_pk_bf16_f32 v6, v162, v164
	v_cvt_pk_bf16_f32 v50, v163, v165
	v_mul_f32_e32 v162, v40, v226
	v_mul_f32_e32 v163, v0, v226
	v_fma_f32 v162, v0, v218, -v162
	v_fmac_f32_e32 v163, v40, v218
	v_mul_f32_e32 v164, v41, v227
	v_mul_f32_e32 v165, v1, v227
	v_fma_f32 v164, v1, v219, -v164
	v_fmac_f32_e32 v165, v41, v219
	v_cvt_pk_bf16_f32 v0, v162, v164
	v_cvt_pk_bf16_f32 v40, v163, v165
	v_mul_f32_e32 v162, v42, v228
	v_mul_f32_e32 v163, v2, v228
	v_fma_f32 v162, v2, v220, -v162
	v_fmac_f32_e32 v163, v42, v220
	v_mul_f32_e32 v164, v43, v229
	v_mul_f32_e32 v165, v3, v229
	v_fma_f32 v164, v3, v221, -v164
	v_fmac_f32_e32 v165, v43, v221
	v_cvt_pk_bf16_f32 v2, v162, v164
	v_cvt_pk_bf16_f32 v42, v163, v165
	s_mov_b64 s[20:21], 0x1800
	global_store_short v[160:161], v124, off offset:256
	global_store_short_d16_hi v[160:161], v124, off offset:640
	global_store_short v[160:161], v116, off offset:320
	global_store_short_d16_hi v[160:161], v116, off offset:704
	global_store_short v[160:161], v126, off offset:1024
	global_store_short_d16_hi v[160:161], v126, off offset:1408
	global_store_short v[160:161], v118, off offset:1088
	global_store_short_d16_hi v[160:161], v118, off offset:1472
	global_store_short v[160:161], v120, off offset:288
	global_store_short_d16_hi v[160:161], v120, off offset:672
	global_store_short v[160:161], v112, off offset:352
	global_store_short_d16_hi v[160:161], v112, off offset:736
	global_store_short v[160:161], v122, off offset:1056
	global_store_short_d16_hi v[160:161], v122, off offset:1440
	global_store_short v[160:161], v114, off offset:1120
	global_store_short_d16_hi v[160:161], v114, off offset:1504
	v_lshl_add_u64 v[160:161], v[160:161], 0, s[20:21]
	global_store_short v[160:161], v108, off offset:256
	global_store_short_d16_hi v[160:161], v108, off offset:640
	global_store_short v[160:161], v100, off offset:320
	global_store_short_d16_hi v[160:161], v100, off offset:704
	global_store_short v[160:161], v110, off offset:1024
	global_store_short_d16_hi v[160:161], v110, off offset:1408
	global_store_short v[160:161], v102, off offset:1088
	global_store_short_d16_hi v[160:161], v102, off offset:1472
	global_store_short v[160:161], v104, off offset:288
	global_store_short_d16_hi v[160:161], v104, off offset:672
	global_store_short v[160:161], v96, off offset:352
	global_store_short_d16_hi v[160:161], v96, off offset:736
	global_store_short v[160:161], v106, off offset:1056
	global_store_short_d16_hi v[160:161], v106, off offset:1440
	global_store_short v[160:161], v98, off offset:1120
	global_store_short_d16_hi v[160:161], v98, off offset:1504
	v_lshl_add_u64 v[160:161], v[160:161], 0, s[20:21]
	global_store_short v[160:161], v92, off offset:256
	global_store_short_d16_hi v[160:161], v92, off offset:640
	global_store_short v[160:161], v84, off offset:320
	global_store_short_d16_hi v[160:161], v84, off offset:704
	global_store_short v[160:161], v94, off offset:1024
	global_store_short_d16_hi v[160:161], v94, off offset:1408
	global_store_short v[160:161], v86, off offset:1088
	global_store_short_d16_hi v[160:161], v86, off offset:1472
	global_store_short v[160:161], v88, off offset:288
	global_store_short_d16_hi v[160:161], v88, off offset:672
	global_store_short v[160:161], v80, off offset:352
	global_store_short_d16_hi v[160:161], v80, off offset:736
	global_store_short v[160:161], v90, off offset:1056
	global_store_short_d16_hi v[160:161], v90, off offset:1440
	global_store_short v[160:161], v82, off offset:1120
	global_store_short_d16_hi v[160:161], v82, off offset:1504
	v_lshl_add_u64 v[160:161], v[160:161], 0, s[20:21]
	global_store_short v[160:161], v76, off offset:256
	global_store_short_d16_hi v[160:161], v76, off offset:640
	global_store_short v[160:161], v68, off offset:320
	global_store_short_d16_hi v[160:161], v68, off offset:704
	global_store_short v[160:161], v78, off offset:1024
	global_store_short_d16_hi v[160:161], v78, off offset:1408
	global_store_short v[160:161], v70, off offset:1088
	global_store_short_d16_hi v[160:161], v70, off offset:1472
	global_store_short v[160:161], v72, off offset:288
	global_store_short_d16_hi v[160:161], v72, off offset:672
	global_store_short v[160:161], v64, off offset:352
	global_store_short_d16_hi v[160:161], v64, off offset:736
	global_store_short v[160:161], v74, off offset:1056
	global_store_short_d16_hi v[160:161], v74, off offset:1440
	global_store_short v[160:161], v66, off offset:1120
	global_store_short_d16_hi v[160:161], v66, off offset:1504
	v_lshl_add_u64 v[160:161], v[160:161], 0, s[20:21]
	global_store_short v[160:161], v60, off offset:256
	global_store_short_d16_hi v[160:161], v60, off offset:640
	global_store_short v[160:161], v52, off offset:320
	global_store_short_d16_hi v[160:161], v52, off offset:704
	global_store_short v[160:161], v62, off offset:1024
	global_store_short_d16_hi v[160:161], v62, off offset:1408
	global_store_short v[160:161], v54, off offset:1088
	global_store_short_d16_hi v[160:161], v54, off offset:1472
	global_store_short v[160:161], v56, off offset:288
	global_store_short_d16_hi v[160:161], v56, off offset:672
	global_store_short v[160:161], v44, off offset:352
	global_store_short_d16_hi v[160:161], v44, off offset:736
	global_store_short v[160:161], v58, off offset:1056
	global_store_short_d16_hi v[160:161], v58, off offset:1440
	global_store_short v[160:161], v46, off offset:1120
	global_store_short_d16_hi v[160:161], v46, off offset:1504
	v_lshl_add_u64 v[160:161], v[160:161], 0, s[20:21]
	global_store_short v[160:161], v36, off offset:256
	global_store_short_d16_hi v[160:161], v36, off offset:640
	global_store_short v[160:161], v28, off offset:320
	global_store_short_d16_hi v[160:161], v28, off offset:704
	global_store_short v[160:161], v38, off offset:1024
	global_store_short_d16_hi v[160:161], v38, off offset:1408
	global_store_short v[160:161], v30, off offset:1088
	global_store_short_d16_hi v[160:161], v30, off offset:1472
	global_store_short v[160:161], v32, off offset:288
	global_store_short_d16_hi v[160:161], v32, off offset:672
	global_store_short v[160:161], v24, off offset:352
	global_store_short_d16_hi v[160:161], v24, off offset:736
	global_store_short v[160:161], v34, off offset:1056
	global_store_short_d16_hi v[160:161], v34, off offset:1440
	global_store_short v[160:161], v26, off offset:1120
	global_store_short_d16_hi v[160:161], v26, off offset:1504
	v_lshl_add_u64 v[160:161], v[160:161], 0, s[20:21]
	global_store_short v[160:161], v20, off offset:256
	global_store_short_d16_hi v[160:161], v20, off offset:640
	global_store_short v[160:161], v12, off offset:320
	global_store_short_d16_hi v[160:161], v12, off offset:704
	global_store_short v[160:161], v22, off offset:1024
	global_store_short_d16_hi v[160:161], v22, off offset:1408
	global_store_short v[160:161], v14, off offset:1088
	global_store_short_d16_hi v[160:161], v14, off offset:1472
	global_store_short v[160:161], v16, off offset:288
	global_store_short_d16_hi v[160:161], v16, off offset:672
	global_store_short v[160:161], v8, off offset:352
	global_store_short_d16_hi v[160:161], v8, off offset:736
	global_store_short v[160:161], v18, off offset:1056
	global_store_short_d16_hi v[160:161], v18, off offset:1440
	global_store_short v[160:161], v10, off offset:1120
	global_store_short_d16_hi v[160:161], v10, off offset:1504
	v_lshl_add_u64 v[160:161], v[160:161], 0, s[20:21]
	global_store_short v[160:161], v4, off offset:256
	global_store_short_d16_hi v[160:161], v4, off offset:640
	global_store_short v[160:161], v48, off offset:320
	global_store_short_d16_hi v[160:161], v48, off offset:704
	global_store_short v[160:161], v6, off offset:1024
	global_store_short_d16_hi v[160:161], v6, off offset:1408
	global_store_short v[160:161], v50, off offset:1088
	global_store_short_d16_hi v[160:161], v50, off offset:1472
	global_store_short v[160:161], v0, off offset:288
	global_store_short_d16_hi v[160:161], v0, off offset:672
	global_store_short v[160:161], v40, off offset:352
	global_store_short_d16_hi v[160:161], v40, off offset:736
	global_store_short v[160:161], v2, off offset:1056
	global_store_short_d16_hi v[160:161], v2, off offset:1440
	global_store_short v[160:161], v42, off offset:1120
	global_store_short_d16_hi v[160:161], v42, off offset:1504
